# v19 + O3 kv-up epilogue: k-norm gain loads and rope gain pairs hoisted out of load->vmcnt(0) chains
# baseline (speedup 1.0000x reference)
.LBB0_505:
	v_lshlrev_b32_e32 v88, 5, v87
	v_mov_b32_e32 v89, v129
	v_lshl_add_u64 v[68:69], v[66:67], 0, v[88:89]
	global_load_dwordx4 v[72:75], v[68:69], off offset:64
	global_load_dwordx4 v[64:67], v[68:69], off offset:80
	global_load_dwordx4 v[76:79], v[68:69], off
	s_nop 0
	global_load_dwordx4 v[68:71], v[68:69], off offset:16
	v_lshlrev_b32_e32 v83, 4, v87
	v_pk_mul_f32 v[92:93], v[40:41], v[86:87] op_sel_hi:[1,0]
	v_pk_mul_f32 v[90:91], v[42:43], v[86:87] op_sel_hi:[1,0]
	v_pk_mul_f32 v[42:43], v[44:45], v[86:87] op_sel_hi:[1,0]
	v_pk_mul_f32 v[40:41], v[46:47], v[86:87] op_sel_hi:[1,0]
	v_pk_mul_f32 v[44:45], v[50:51], v[86:87] op_sel_hi:[1,0]
	v_pk_mul_f32 v[46:47], v[48:49], v[86:87] op_sel_hi:[1,0]
	v_pk_mul_f32 v[48:49], v[54:55], v[86:87] op_sel_hi:[1,0]
	v_pk_mul_f32 v[50:51], v[52:53], v[86:87] op_sel_hi:[1,0]
	v_pk_mul_f32 v[52:53], v[58:59], v[86:87] op_sel_hi:[1,0]
	v_pk_mul_f32 v[54:55], v[56:57], v[86:87] op_sel_hi:[1,0]
	v_pk_mul_f32 v[56:57], v[62:63], v[86:87] op_sel_hi:[1,0]
	v_pk_mul_f32 v[58:59], v[60:61], v[86:87] op_sel_hi:[1,0]
	v_pk_mul_f32 v[60:61], v[34:35], v[86:87] op_sel_hi:[1,0]
	v_pk_mul_f32 v[62:63], v[32:33], v[86:87] op_sel_hi:[1,0]
	global_load_dwordx4 v[198:201], v83, s[40:41]
	global_load_dwordx4 v[202:205], v83, s[40:41] offset:32
	global_load_dwordx4 v[206:209], v83, s[40:41] offset:64
	global_load_dwordx4 v[210:213], v83, s[40:41] offset:96
	global_load_dwordx4 v[214:217], v83, s[40:41] offset:128
	global_load_dwordx4 v[218:221], v83, s[40:41] offset:160
	global_load_dwordx4 v[222:225], v83, s[40:41] offset:192
	global_load_dwordx4 v[226:229], v83, s[40:41] offset:224
	v_pk_mul_f32 v[96:97], v[36:37], v[86:87] op_sel_hi:[1,0]
	v_mul_f32_e32 v36, v47, v47
	v_pk_fma_f32 v[36:37], v[46:47], v[46:47], v[36:37] op_sel_hi:[1,1,0]
	v_mul_f32_e32 v98, v45, v45
	v_pk_fma_f32 v[36:37], v[44:45], v[44:45], v[36:37]
	v_mul_f32_e32 v100, v51, v51
	v_pk_add_f32 v[36:37], v[98:99], v[36:37] op_sel_hi:[0,1]
	v_pk_fma_f32 v[36:37], v[50:51], v[50:51], v[36:37]
	v_mul_f32_e32 v102, v49, v49
	v_pk_add_f32 v[36:37], v[100:101], v[36:37] op_sel_hi:[0,1]
	v_pk_fma_f32 v[36:37], v[48:49], v[48:49], v[36:37]
	v_mul_f32_e32 v104, v55, v55
	v_pk_add_f32 v[36:37], v[102:103], v[36:37] op_sel_hi:[0,1]
	v_pk_fma_f32 v[36:37], v[54:55], v[54:55], v[36:37]
	v_mul_f32_e32 v106, v53, v53
	v_pk_add_f32 v[36:37], v[104:105], v[36:37] op_sel_hi:[0,1]
	v_pk_fma_f32 v[36:37], v[52:53], v[52:53], v[36:37]
	v_mul_f32_e32 v108, v59, v59
	v_pk_add_f32 v[36:37], v[106:107], v[36:37] op_sel_hi:[0,1]
	v_pk_fma_f32 v[36:37], v[58:59], v[58:59], v[36:37]
	v_mul_f32_e32 v110, v57, v57
	v_pk_add_f32 v[36:37], v[108:109], v[36:37] op_sel_hi:[0,1]
	v_pk_fma_f32 v[36:37], v[56:57], v[56:57], v[36:37]
	v_mul_f32_e32 v112, v63, v63
	v_pk_add_f32 v[36:37], v[110:111], v[36:37] op_sel_hi:[0,1]
	v_pk_fma_f32 v[36:37], v[62:63], v[62:63], v[36:37]
	v_mul_f32_e32 v114, v61, v61
	v_pk_add_f32 v[36:37], v[112:113], v[36:37] op_sel_hi:[0,1]
	v_pk_fma_f32 v[36:37], v[60:61], v[60:61], v[36:37]
	v_mul_f32_e32 v116, v97, v97
	v_pk_add_f32 v[36:37], v[114:115], v[36:37] op_sel_hi:[0,1]
	v_pk_fma_f32 v[36:37], v[96:97], v[96:97], v[36:37]
	v_pk_mul_f32 v[38:39], v[38:39], v[86:87] op_sel_hi:[1,0]
	v_pk_add_f32 v[36:37], v[116:117], v[36:37] op_sel_hi:[0,1]
	v_mul_f32_e32 v118, v39, v39
	v_pk_fma_f32 v[36:37], v[38:39], v[38:39], v[36:37]
	v_mul_f32_e32 v120, v93, v93
	v_pk_add_f32 v[36:37], v[118:119], v[36:37] op_sel_hi:[0,1]
	v_pk_fma_f32 v[36:37], v[92:93], v[92:93], v[36:37]
	v_mul_f32_e32 v122, v91, v91
	v_pk_add_f32 v[36:37], v[120:121], v[36:37] op_sel_hi:[0,1]
	v_pk_fma_f32 v[36:37], v[90:91], v[90:91], v[36:37]
	v_mul_f32_e32 v124, v43, v43
	v_pk_add_f32 v[36:37], v[122:123], v[36:37] op_sel_hi:[0,1]
	v_pk_fma_f32 v[36:37], v[42:43], v[42:43], v[36:37]
	v_mul_f32_e32 v126, v41, v41
	v_pk_add_f32 v[36:37], v[124:125], v[36:37] op_sel_hi:[0,1]
	v_pk_fma_f32 v[36:37], v[40:41], v[40:41], v[36:37]
	s_mov_b32 s2, 0x800000
	v_pk_add_f32 v[36:37], v[126:127], v[36:37] op_sel_hi:[0,1]
	v_mov_b32_e32 v98, v36
	s_nop 1
	v_permlane32_swap_b32_e32 v36, v98
	v_lshlrev_b32_e32 v128, 3, v87
	s_waitcnt vmcnt(11)
	v_pk_mul_f32 v[102:103], v[72:73], v[72:73]
	v_pk_mul_f32 v[100:101], v[74:75], v[74:75]
	s_waitcnt vmcnt(9)
	v_pk_fma_f32 v[102:103], v[76:77], v[76:77], v[102:103]
	v_pk_fma_f32 v[100:101], v[78:79], v[78:79], v[100:101]
	v_pk_add_f32 v[102:103], v[102:103], v[102:103] op_sel:[0,1] op_sel_hi:[1,0]
	v_pk_mul_f32 v[106:107], v[64:65], v[64:65]
	v_pk_add_f32 v[102:103], v[100:101], v[102:103]
	s_waitcnt vmcnt(8)
	v_pk_fma_f32 v[106:107], v[68:69], v[68:69], v[106:107]
	v_pk_add_f32 v[100:101], v[100:101], v[102:103] op_sel:[1,0] op_sel_hi:[0,1]
	v_pk_mul_f32 v[104:105], v[66:67], v[66:67]
	v_pk_add_f32 v[100:101], v[106:107], v[100:101]
	v_pk_fma_f32 v[104:105], v[70:71], v[70:71], v[104:105]
	v_pk_add_f32 v[100:101], v[106:107], v[100:101] op_sel:[1,0] op_sel_hi:[0,1]
	v_pk_add_f32 v[100:101], v[104:105], v[100:101]
	s_nop 0
	v_pk_add_f32 v[100:101], v[104:105], v[100:101] op_sel:[1,0] op_sel_hi:[0,1]
	v_mov_b32_e32 v99, v100
	s_nop 1
	v_permlane32_swap_b32_e32 v100, v99
	v_mov_b32_e32 v37, v100
	v_pk_add_f32 v[36:37], v[36:37], v[98:99]
	v_lshl_add_u64 v[98:99], v[84:85], 0, v[128:129]
	v_add_f32_e32 v36, v36, v37
	v_fmamk_f32 v36, v36, 0x3c2aaaab, v163
	v_mul_f32_e32 v37, 0x4b800000, v36
	v_cmp_gt_f32_e32 vcc, s2, v36
	s_nop 1
	v_cndmask_b32_e32 v36, v36, v37, vcc
	v_rsq_f32_e32 v36, v36
	s_nop 0
	v_mul_f32_e32 v37, 0x45800000, v36
	v_cndmask_b32_e32 v36, v36, v37, vcc
	v_pk_mul_f32 v[46:47], v[46:47], v[36:37] op_sel_hi:[1,0]
	v_pk_mul_f32 v[44:45], v[44:45], v[36:37] op_sel_hi:[1,0]
	s_waitcnt vmcnt(7)
	v_pk_mul_f32 v[32:33], v[198:199], v[46:47]
	v_pk_mul_f32 v[34:35], v[200:201], v[44:45]
	v_cvt_pk_bf16_f32 v32, v32, v33
	v_cvt_pk_bf16_f32 v33, v34, v35
	global_store_dwordx2 v[98:99], v[32:33], off
	v_pk_mul_f32 v[44:45], v[50:51], v[36:37] op_sel_hi:[1,0]
	v_pk_mul_f32 v[46:47], v[48:49], v[36:37] op_sel_hi:[1,0]
	v_pk_mul_f32 v[38:39], v[38:39], v[36:37] op_sel_hi:[1,0]
	v_pk_mul_f32 v[40:41], v[40:41], v[36:37] op_sel_hi:[1,0]
	v_cmp_gt_u32_e32 vcc, 32, v94
	s_waitcnt vmcnt(7)
	v_pk_mul_f32 v[32:33], v[202:203], v[44:45]
	v_pk_mul_f32 v[34:35], v[204:205], v[46:47]
	v_cvt_pk_bf16_f32 v32, v32, v33
	v_cvt_pk_bf16_f32 v33, v34, v35
	global_store_dwordx2 v[98:99], v[32:33], off offset:16
	v_pk_mul_f32 v[44:45], v[54:55], v[36:37] op_sel_hi:[1,0]
	v_pk_mul_f32 v[46:47], v[52:53], v[36:37] op_sel_hi:[1,0]
	s_waitcnt vmcnt(7)
	v_pk_mul_f32 v[32:33], v[206:207], v[44:45]
	v_pk_mul_f32 v[34:35], v[208:209], v[46:47]
	v_cvt_pk_bf16_f32 v32, v32, v33
	v_cvt_pk_bf16_f32 v33, v34, v35
	global_store_dwordx2 v[98:99], v[32:33], off offset:32
	v_pk_mul_f32 v[44:45], v[58:59], v[36:37] op_sel_hi:[1,0]
	v_pk_mul_f32 v[46:47], v[56:57], v[36:37] op_sel_hi:[1,0]
	s_waitcnt vmcnt(7)
	v_pk_mul_f32 v[32:33], v[210:211], v[44:45]
	v_pk_mul_f32 v[34:35], v[212:213], v[46:47]
	v_cvt_pk_bf16_f32 v32, v32, v33
	v_cvt_pk_bf16_f32 v33, v34, v35
	global_store_dwordx2 v[98:99], v[32:33], off offset:48
	v_pk_mul_f32 v[44:45], v[62:63], v[36:37] op_sel_hi:[1,0]
	v_pk_mul_f32 v[46:47], v[60:61], v[36:37] op_sel_hi:[1,0]
	s_waitcnt vmcnt(7)
	v_pk_mul_f32 v[32:33], v[214:215], v[44:45]
	v_pk_mul_f32 v[34:35], v[216:217], v[46:47]
	v_cvt_pk_bf16_f32 v32, v32, v33
	v_cvt_pk_bf16_f32 v33, v34, v35
	global_store_dwordx2 v[98:99], v[32:33], off offset:64
	v_pk_mul_f32 v[44:45], v[96:97], v[36:37] op_sel_hi:[1,0]
	s_waitcnt vmcnt(7)
	v_pk_mul_f32 v[34:35], v[38:39], v[220:221]
	v_pk_mul_f32 v[32:33], v[44:45], v[218:219]
	v_pk_mul_f32 v[38:39], v[92:93], v[36:37] op_sel_hi:[1,0]
	v_cvt_pk_bf16_f32 v32, v32, v33
	v_cvt_pk_bf16_f32 v33, v34, v35
	global_store_dwordx2 v[98:99], v[32:33], off offset:80
	v_pk_mul_f32 v[44:45], v[90:91], v[36:37] op_sel_hi:[1,0]
	s_waitcnt vmcnt(7)
	v_pk_mul_f32 v[32:33], v[38:39], v[222:223]
	v_pk_mul_f32 v[34:35], v[44:45], v[224:225]
	v_cvt_pk_bf16_f32 v32, v32, v33
	v_cvt_pk_bf16_f32 v33, v34, v35
	global_store_dwordx2 v[98:99], v[32:33], off offset:96
	v_pk_mul_f32 v[38:39], v[42:43], v[36:37] op_sel_hi:[1,0]
	s_waitcnt vmcnt(7)
	v_pk_mul_f32 v[34:35], v[40:41], v[228:229]
	v_pk_mul_f32 v[32:33], v[38:39], v[226:227]
	s_nop 0
	v_cvt_pk_bf16_f32 v32, v32, v33
	v_cvt_pk_bf16_f32 v33, v34, v35
	global_store_dwordx2 v[98:99], v[32:33], off offset:112
	global_load_dwordx2 v[44:45], v88, s[40:41] offset:320
	global_load_dwordx2 v[46:47], v88, s[40:41] offset:256
	v_lshrrev_b32_e32 v32, 6, v95
	v_and_b32_e32 v33, 63, v95
	v_cndmask_b32_e32 v32, v33, v32, vcc
	v_cvt_f32_u32_e32 v52, v32
	v_mov_b32_e32 v32, v73
	v_mov_b32_e32 v33, v77
	v_pk_mul_f32 v[32:33], v[32:33], v[36:37] op_sel_hi:[1,0]
	s_waitcnt vmcnt(1)
	v_mov_b32_e32 v34, v45
	s_waitcnt vmcnt(0)
	v_mov_b32_e32 v35, v47
	v_pk_mul_f32 v[32:33], v[32:33], v[34:35]
	s_and_saveexec_b64 s[2:3], s[0:1]
	s_cbranch_execz .LBB0_507
	v_mul_f32_e32 v34, v156, v52
	v_mul_f32_e32 v35, 0.15915494, v34
	v_sin_f32_e32 v38, v35
	v_cos_f32_e32 v34, v35
	v_pk_mul_f32 v[38:39], v[38:39], v[32:33] op_sel:[0,1] op_sel_hi:[0,0]
	v_pk_mul_f32 v[40:41], v[34:35], v[32:33] op_sel_hi:[0,1]
	v_pk_fma_f32 v[32:33], v[34:35], v[32:33], v[38:39] op_sel_hi:[0,1,1] neg_lo:[0,0,1] neg_hi:[0,0,1]
	v_add_f32_e32 v32, v40, v38
.LBB0_507:
	s_or_b64 exec, exec, s[2:3]
	v_lshl_add_u64 v[48:49], s[40:41], 0, v[88:89]
	global_load_dword v185, v[48:49], off offset:264
	global_load_dword v184, v[48:49], off offset:328
	global_load_dword v187, v[48:49], off offset:268
	global_load_dword v186, v[48:49], off offset:332
	global_load_dword v189, v[48:49], off offset:272
	global_load_dword v188, v[48:49], off offset:336
	global_load_dword v191, v[48:49], off offset:276
	global_load_dword v190, v[48:49], off offset:340
	global_load_dword v193, v[48:49], off offset:280
	global_load_dword v192, v[48:49], off offset:344
	v_mov_b32_e32 v37, v36
	v_mov_b32_e32 v38, v74
	v_mov_b32_e32 v39, v78
	v_pk_mul_f32 v[38:39], v[38:39], v[36:37]
	s_waitcnt vmcnt(8)
	v_pk_mul_f32 v[34:35], v[38:39], v[184:185]
	s_and_saveexec_b64 s[2:3], s[0:1]
	s_cbranch_execz .LBB0_509
	v_mul_f32_e32 v38, v157, v52
	v_mul_f32_e32 v39, 0.15915494, v38
	v_sin_f32_e32 v40, v39
	v_cos_f32_e32 v38, v39
	v_pk_mul_f32 v[40:41], v[40:41], v[34:35] op_sel:[0,1] op_sel_hi:[0,0]
	v_pk_mul_f32 v[42:43], v[38:39], v[34:35] op_sel_hi:[0,1]
	v_pk_fma_f32 v[34:35], v[38:39], v[34:35], v[40:41] op_sel_hi:[0,1,1] neg_lo:[0,0,1] neg_hi:[0,0,1]
	v_add_f32_e32 v34, v42, v40
.LBB0_509:
	s_or_b64 exec, exec, s[2:3]
	v_mov_b32_e32 v78, v75
	v_pk_mul_f32 v[40:41], v[78:79], v[36:37]
	s_waitcnt vmcnt(6)
	v_pk_mul_f32 v[38:39], v[40:41], v[186:187]
	s_and_saveexec_b64 s[2:3], s[0:1]
	s_cbranch_execz .LBB0_511
	v_mul_f32_e32 v40, v158, v52
	v_mul_f32_e32 v41, 0.15915494, v40
	v_sin_f32_e32 v42, v41
	v_cos_f32_e32 v40, v41
	v_pk_mul_f32 v[42:43], v[42:43], v[38:39] op_sel:[0,1] op_sel_hi:[0,0]
	v_pk_mul_f32 v[50:51], v[40:41], v[38:39] op_sel_hi:[0,1]
	v_pk_fma_f32 v[38:39], v[40:41], v[38:39], v[42:43] op_sel_hi:[0,1,1] neg_lo:[0,0,1] neg_hi:[0,0,1]
	v_add_f32_e32 v38, v50, v42
.LBB0_511:
	s_or_b64 exec, exec, s[2:3]
	v_mov_b32_e32 v42, v64
	v_mov_b32_e32 v43, v68
	v_pk_mul_f32 v[42:43], v[42:43], v[36:37]
	s_waitcnt vmcnt(4)
	v_pk_mul_f32 v[40:41], v[42:43], v[188:189]
	s_and_saveexec_b64 s[2:3], s[0:1]
	s_cbranch_execz .LBB0_513
	v_mul_f32_e32 v42, v159, v52
	v_mul_f32_e32 v43, 0.15915494, v42
	v_sin_f32_e32 v50, v43
	v_cos_f32_e32 v42, v43
	v_pk_mul_f32 v[50:51], v[50:51], v[40:41] op_sel:[0,1] op_sel_hi:[0,0]
	v_pk_mul_f32 v[54:55], v[42:43], v[40:41] op_sel_hi:[0,1]
	v_pk_fma_f32 v[40:41], v[42:43], v[40:41], v[50:51] op_sel_hi:[0,1,1] neg_lo:[0,0,1] neg_hi:[0,0,1]
	v_add_f32_e32 v40, v54, v50
.LBB0_513:
	s_or_b64 exec, exec, s[2:3]
	v_mov_b32_e32 v68, v65
	v_pk_mul_f32 v[50:51], v[68:69], v[36:37]
	s_waitcnt vmcnt(2)
	v_pk_mul_f32 v[42:43], v[50:51], v[190:191]
	s_and_saveexec_b64 s[2:3], s[0:1]
	s_cbranch_execz .LBB0_515
	v_mul_f32_e32 v45, v160, v52
	v_mul_f32_e32 v45, 0.15915494, v45
	v_sin_f32_e32 v54, v45
	v_cos_f32_e32 v50, v45
	v_pk_mul_f32 v[54:55], v[54:55], v[42:43] op_sel:[0,1] op_sel_hi:[0,0]
	v_pk_mul_f32 v[56:57], v[50:51], v[42:43] op_sel_hi:[0,1]
	v_pk_fma_f32 v[42:43], v[50:51], v[42:43], v[54:55] op_sel_hi:[0,1,1] neg_lo:[0,0,1] neg_hi:[0,0,1]
	v_add_f32_e32 v42, v56, v54
.LBB0_515:
	s_or_b64 exec, exec, s[2:3]
	v_mov_b32_e32 v54, v66
	v_mov_b32_e32 v55, v70
	v_pk_mul_f32 v[54:55], v[54:55], v[36:37]
	s_waitcnt vmcnt(0)
	v_pk_mul_f32 v[50:51], v[54:55], v[192:193]
	s_and_saveexec_b64 s[2:3], s[0:1]
	s_cbranch_execz .LBB0_517
	v_mul_f32_e32 v45, v161, v52
	v_mul_f32_e32 v45, 0.15915494, v45
	v_sin_f32_e32 v56, v45
	v_cos_f32_e32 v54, v45
	v_pk_mul_f32 v[56:57], v[56:57], v[50:51] op_sel:[0,1] op_sel_hi:[0,0]
	v_pk_mul_f32 v[58:59], v[54:55], v[50:51] op_sel_hi:[0,1]
	v_pk_fma_f32 v[50:51], v[54:55], v[50:51], v[56:57] op_sel_hi:[0,1,1] neg_lo:[0,0,1] neg_hi:[0,0,1]
	v_add_f32_e32 v50, v58, v56
